# in-projection epilogue (U / x_lru / gelu gate) hand-written with packed f32 math and three straight-line segment variants
# baseline (speedup 1.0000x reference)
; __device__ __forceinline__ float fgelu(float x) { return x * fsigmoid(1.5957691216057308f * (x + 0.044715f * x * x * x)); }
; __device__ __forceinline__ u32x4 pack8(const f32x4 a, const f32x4 b) { u32x4 w; w.x = cvt_pk_bf16(a[0], a[1]); w.y = cvt_pk_bf16(a[2], a[3]); w.z = cvt_pk_bf16(b[0], b[1]); w.w = cvt_pk_bf16(b[2], b[3]); return w; }
;     __device__ __forceinline__ void operator()(const Acc& acc, const Unit& u, int wr, int wc, int fr, int fq) const {
;         int row0 = u.pm * BM + wr * 64 + fr, col0 = (u.pn & 3) * BM + wc * 32 + 8 * fq; const int seg = u.pn >> 2; asm volatile("" : "+v"(row0), "+v"(col0));
;         float sq[2][4];
; #pragma unroll
;         for (int ai = 0; ai < 2; ++ai)
; #pragma unroll
;             for (int m = 0; m < 4; ++m) sq[ai][m] = ssq[row0 + ai * HALF + m * 16];
;         asm volatile("" ::: "memory");
; #pragma unroll
;         for (int ai = 0; ai < 2; ++ai)
; #pragma unroll
;             for (int m = 0; m < 4; ++m) {
;                 const int row = row0 + ai * HALF + m * 16;
;                 const float r = rsqrtf(sq[ai][m] * (1.0f / D) + EPS);
; #pragma unroll
;                 for (int bj = 0; bj < 2; ++bj) {
;                     const size_t o = (size_t)row * DH + col0 + bj * HALF;
;                     f32x4 v0 = acc[ai][bj][m][0] * r, v1 = acc[ai][bj][m][1] * r;
;                     if (seg == 0) { *(u32x4*)(U + o) = pack8(v0, v1); }
;                     else if (seg == 1) { *(f32x4*)(XL + o) = v0; *(f32x4*)(XL + o + 4) = v1; }
;                     else {
; #pragma unroll
;                         for (int j = 0; j < 4; ++j) { v0[j] = fgelu(v0[j]); v1[j] = fgelu(v1[j]); }
;                         *(u32x4*)(GG + o) = pack8(v0, v1);
;                     }
.LBB0_367:
	v_lshl_add_u32 v132, s4, 8, v144
	s_lshl_b32 s4, s17, 8
	s_and_b32 s4, s4, 0x300
	v_or_b32_e32 v133, s4, v147
	v_lshlrev_b32_e32 v134, 2, v132
	global_load_dword v150, v134, s[50:51]
	global_load_dword v151, v134, s[50:51] offset:64
	global_load_dword v152, v134, s[50:51] offset:128
	global_load_dword v153, v134, s[50:51] offset:192
	global_load_dword v154, v134, s[50:51] offset:512
	global_load_dword v155, v134, s[50:51] offset:576
	global_load_dword v156, v134, s[50:51] offset:640
	global_load_dword v157, v134, s[50:51] offset:704
	v_lshl_or_b32 v135, v132, 10, v133
	s_lshr_b32 s6, s17, 2
	s_waitcnt vmcnt(0)
	v_fmamk_f32 v158, v150, 0x3a000000, v149
	v_fmamk_f32 v160, v151, 0x3a000000, v149
	v_fmamk_f32 v162, v152, 0x3a000000, v149
	v_fmamk_f32 v164, v153, 0x3a000000, v149
	v_fmamk_f32 v166, v154, 0x3a000000, v149
	v_fmamk_f32 v168, v155, 0x3a000000, v149
	v_fmamk_f32 v170, v156, 0x3a000000, v149
	v_fmamk_f32 v172, v157, 0x3a000000, v149
	v_rsq_f32_e32 v158, v158
	v_rsq_f32_e32 v160, v160
	v_rsq_f32_e32 v162, v162
	v_rsq_f32_e32 v164, v164
	v_rsq_f32_e32 v166, v166
	v_rsq_f32_e32 v168, v168
	v_rsq_f32_e32 v170, v170
	v_rsq_f32_e32 v172, v172
	s_cmp_eq_u32 s6, 0
	s_cbranch_scc1 .Lep3_u
	s_cmp_eq_u32 s6, 1
	s_cbranch_scc1 .Lep3_xl
	v_readlane_b32 s8, v254, 63
	v_readlane_b32 s9, v253, 0
	v_mov_b32_e32 v174, 0xc0135761
	v_mov_b32_e32 v176, 0xbdd2d3e8
	v_mov_b32_e32 v178, 1.0
	v_mov_b32_e32 v179, 1.0
	v_lshlrev_b32_e32 v136, 1, v135
	v_pk_mul_f32 v[126:127], v[126:127], v[158:159] op_sel_hi:[1,0]
	v_pk_mul_f32 v[128:129], v[128:129], v[158:159] op_sel_hi:[1,0]
	v_pk_mul_f32 v[122:123], v[122:123], v[158:159] op_sel_hi:[1,0]
	v_pk_mul_f32 v[124:125], v[124:125], v[158:159] op_sel_hi:[1,0]
	v_pk_mul_f32 v[184:185], v[126:127], v[126:127]
	v_pk_mul_f32 v[186:187], v[128:129], v[128:129]
	v_pk_mul_f32 v[188:189], v[122:123], v[122:123]
	v_pk_mul_f32 v[190:191], v[124:125], v[124:125]
	v_pk_fma_f32 v[184:185], v[184:185], v[176:177], v[174:175] op_sel_hi:[1,0,0]
	v_pk_fma_f32 v[186:187], v[186:187], v[176:177], v[174:175] op_sel_hi:[1,0,0]
	v_pk_fma_f32 v[188:189], v[188:189], v[176:177], v[174:175] op_sel_hi:[1,0,0]
	v_pk_fma_f32 v[190:191], v[190:191], v[176:177], v[174:175] op_sel_hi:[1,0,0]
	v_pk_mul_f32 v[184:185], v[184:185], v[126:127]
	v_pk_mul_f32 v[186:187], v[186:187], v[128:129]
	v_pk_mul_f32 v[188:189], v[188:189], v[122:123]
	v_pk_mul_f32 v[190:191], v[190:191], v[124:125]
	v_exp_f32_e32 v184, v184
	v_exp_f32_e32 v185, v185
	v_exp_f32_e32 v186, v186
	v_exp_f32_e32 v187, v187
	v_exp_f32_e32 v188, v188
	v_exp_f32_e32 v189, v189
	v_exp_f32_e32 v190, v190
	v_exp_f32_e32 v191, v191
	v_pk_add_f32 v[184:185], v[184:185], v[178:179]
	v_pk_add_f32 v[186:187], v[186:187], v[178:179]
	v_pk_add_f32 v[188:189], v[188:189], v[178:179]
	v_pk_add_f32 v[190:191], v[190:191], v[178:179]
	v_rcp_f32_e32 v184, v184
	v_rcp_f32_e32 v185, v185
	v_rcp_f32_e32 v186, v186
	v_rcp_f32_e32 v187, v187
	v_rcp_f32_e32 v188, v188
	v_rcp_f32_e32 v189, v189
	v_rcp_f32_e32 v190, v190
	v_rcp_f32_e32 v191, v191
	v_pk_mul_f32 v[126:127], v[126:127], v[184:185]
	v_pk_mul_f32 v[128:129], v[128:129], v[186:187]
	v_pk_mul_f32 v[122:123], v[122:123], v[188:189]
	v_pk_mul_f32 v[124:125], v[124:125], v[190:191]
	v_cvt_pk_bf16_f32 v126, v126, v127
	v_cvt_pk_bf16_f32 v127, v128, v129
	v_cvt_pk_bf16_f32 v128, v122, v123
	v_cvt_pk_bf16_f32 v129, v124, v125
	global_store_dwordx4 v136, v[126:129], s[8:9]
	v_pk_mul_f32 v[118:119], v[118:119], v[158:159] op_sel_hi:[1,0]
	v_pk_mul_f32 v[120:121], v[120:121], v[158:159] op_sel_hi:[1,0]
	v_pk_mul_f32 v[114:115], v[114:115], v[158:159] op_sel_hi:[1,0]
	v_pk_mul_f32 v[116:117], v[116:117], v[158:159] op_sel_hi:[1,0]
	v_pk_mul_f32 v[184:185], v[118:119], v[118:119]
	v_pk_mul_f32 v[186:187], v[120:121], v[120:121]
	v_pk_mul_f32 v[188:189], v[114:115], v[114:115]
	v_pk_mul_f32 v[190:191], v[116:117], v[116:117]
	v_pk_fma_f32 v[184:185], v[184:185], v[176:177], v[174:175] op_sel_hi:[1,0,0]
	v_pk_fma_f32 v[186:187], v[186:187], v[176:177], v[174:175] op_sel_hi:[1,0,0]
	v_pk_fma_f32 v[188:189], v[188:189], v[176:177], v[174:175] op_sel_hi:[1,0,0]
	v_pk_fma_f32 v[190:191], v[190:191], v[176:177], v[174:175] op_sel_hi:[1,0,0]
	v_pk_mul_f32 v[184:185], v[184:185], v[118:119]
	v_pk_mul_f32 v[186:187], v[186:187], v[120:121]
	v_pk_mul_f32 v[188:189], v[188:189], v[114:115]
	v_pk_mul_f32 v[190:191], v[190:191], v[116:117]
	v_exp_f32_e32 v184, v184
	v_exp_f32_e32 v185, v185
	v_exp_f32_e32 v186, v186
	v_exp_f32_e32 v187, v187
	v_exp_f32_e32 v188, v188
	v_exp_f32_e32 v189, v189
	v_exp_f32_e32 v190, v190
	v_exp_f32_e32 v191, v191
	v_pk_add_f32 v[184:185], v[184:185], v[178:179]
	v_pk_add_f32 v[186:187], v[186:187], v[178:179]
	v_pk_add_f32 v[188:189], v[188:189], v[178:179]
	v_pk_add_f32 v[190:191], v[190:191], v[178:179]
	v_rcp_f32_e32 v184, v184
	v_rcp_f32_e32 v185, v185
	v_rcp_f32_e32 v186, v186
	v_rcp_f32_e32 v187, v187
	v_rcp_f32_e32 v188, v188
	v_rcp_f32_e32 v189, v189
	v_rcp_f32_e32 v190, v190
	v_rcp_f32_e32 v191, v191
	v_pk_mul_f32 v[118:119], v[118:119], v[184:185]
	v_pk_mul_f32 v[120:121], v[120:121], v[186:187]
	v_pk_mul_f32 v[114:115], v[114:115], v[188:189]
	v_pk_mul_f32 v[116:117], v[116:117], v[190:191]
	v_cvt_pk_bf16_f32 v118, v118, v119
	v_cvt_pk_bf16_f32 v119, v120, v121
	v_cvt_pk_bf16_f32 v120, v114, v115
	v_cvt_pk_bf16_f32 v121, v116, v117
	v_add_u32_e32 v138, 0x100, v136
	global_store_dwordx4 v138, v[118:121], s[8:9]
	v_pk_mul_f32 v[110:111], v[110:111], v[160:161] op_sel_hi:[1,0]
	v_pk_mul_f32 v[112:113], v[112:113], v[160:161] op_sel_hi:[1,0]
	v_pk_mul_f32 v[106:107], v[106:107], v[160:161] op_sel_hi:[1,0]
; __device__ __forceinline__ float fgelu(float x) { return x * fsigmoid(1.5957691216057308f * (x + 0.044715f * x * x * x)); }
; __device__ __forceinline__ u32x4 pack8(const f32x4 a, const f32x4 b) { u32x4 w; w.x = cvt_pk_bf16(a[0], a[1]); w.y = cvt_pk_bf16(a[2], a[3]); w.z = cvt_pk_bf16(b[0], b[1]); w.w = cvt_pk_bf16(b[2], b[3]); return w; }
;     __device__ __forceinline__ void operator()(const Acc& acc, const Unit& u, int wr, int wc, int fr, int fq) const {
;     ...
; #pragma unroll
;                 for (int bj = 0; bj < 2; ++bj) {
;                     const size_t o = (size_t)row * DH + col0 + bj * HALF;
;                     f32x4 v0 = acc[ai][bj][m][0] * r, v1 = acc[ai][bj][m][1] * r;
;                     if (seg == 0) { *(u32x4*)(U + o) = pack8(v0, v1); }
;                     else if (seg == 1) { *(f32x4*)(XL + o) = v0; *(f32x4*)(XL + o + 4) = v1; }
;                     else {
; #pragma unroll
;                         for (int j = 0; j < 4; ++j) { v0[j] = fgelu(v0[j]); v1[j] = fgelu(v1[j]); }
;                         *(u32x4*)(GG + o) = pack8(v0, v1);
	v_pk_mul_f32 v[108:109], v[108:109], v[160:161] op_sel_hi:[1,0]
	v_pk_mul_f32 v[184:185], v[110:111], v[110:111]
	v_pk_mul_f32 v[186:187], v[112:113], v[112:113]
	v_pk_mul_f32 v[188:189], v[106:107], v[106:107]
	v_pk_mul_f32 v[190:191], v[108:109], v[108:109]
	v_pk_fma_f32 v[184:185], v[184:185], v[176:177], v[174:175] op_sel_hi:[1,0,0]
	v_pk_fma_f32 v[186:187], v[186:187], v[176:177], v[174:175] op_sel_hi:[1,0,0]
	v_pk_fma_f32 v[188:189], v[188:189], v[176:177], v[174:175] op_sel_hi:[1,0,0]
	v_pk_fma_f32 v[190:191], v[190:191], v[176:177], v[174:175] op_sel_hi:[1,0,0]
	v_pk_mul_f32 v[184:185], v[184:185], v[110:111]
	v_pk_mul_f32 v[186:187], v[186:187], v[112:113]
	v_pk_mul_f32 v[188:189], v[188:189], v[106:107]
	v_pk_mul_f32 v[190:191], v[190:191], v[108:109]
	v_exp_f32_e32 v184, v184
	v_exp_f32_e32 v185, v185
	v_exp_f32_e32 v186, v186
	v_exp_f32_e32 v187, v187
	v_exp_f32_e32 v188, v188
	v_exp_f32_e32 v189, v189
	v_exp_f32_e32 v190, v190
	v_exp_f32_e32 v191, v191
	v_pk_add_f32 v[184:185], v[184:185], v[178:179]
	v_pk_add_f32 v[186:187], v[186:187], v[178:179]
	v_pk_add_f32 v[188:189], v[188:189], v[178:179]
	v_pk_add_f32 v[190:191], v[190:191], v[178:179]
	v_rcp_f32_e32 v184, v184
	v_rcp_f32_e32 v185, v185
	v_rcp_f32_e32 v186, v186
	v_rcp_f32_e32 v187, v187
	v_rcp_f32_e32 v188, v188
	v_rcp_f32_e32 v189, v189
	v_rcp_f32_e32 v190, v190
	v_rcp_f32_e32 v191, v191
	v_pk_mul_f32 v[110:111], v[110:111], v[184:185]
	v_pk_mul_f32 v[112:113], v[112:113], v[186:187]
	v_pk_mul_f32 v[106:107], v[106:107], v[188:189]
	v_pk_mul_f32 v[108:109], v[108:109], v[190:191]
	v_cvt_pk_bf16_f32 v110, v110, v111
	v_cvt_pk_bf16_f32 v111, v112, v113
	v_cvt_pk_bf16_f32 v112, v106, v107
	v_cvt_pk_bf16_f32 v113, v108, v109
	v_add_u32_e32 v137, 0x8000, v136
	global_store_dwordx4 v137, v[110:113], s[8:9]
	v_pk_mul_f32 v[102:103], v[102:103], v[160:161] op_sel_hi:[1,0]
	v_pk_mul_f32 v[104:105], v[104:105], v[160:161] op_sel_hi:[1,0]
	v_pk_mul_f32 v[98:99], v[98:99], v[160:161] op_sel_hi:[1,0]
	v_pk_mul_f32 v[100:101], v[100:101], v[160:161] op_sel_hi:[1,0]
	v_pk_mul_f32 v[184:185], v[102:103], v[102:103]
	v_pk_mul_f32 v[186:187], v[104:105], v[104:105]
	v_pk_mul_f32 v[188:189], v[98:99], v[98:99]
	v_pk_mul_f32 v[190:191], v[100:101], v[100:101]
	v_pk_fma_f32 v[184:185], v[184:185], v[176:177], v[174:175] op_sel_hi:[1,0,0]
	v_pk_fma_f32 v[186:187], v[186:187], v[176:177], v[174:175] op_sel_hi:[1,0,0]
	v_pk_fma_f32 v[188:189], v[188:189], v[176:177], v[174:175] op_sel_hi:[1,0,0]
	v_pk_fma_f32 v[190:191], v[190:191], v[176:177], v[174:175] op_sel_hi:[1,0,0]
	v_pk_mul_f32 v[184:185], v[184:185], v[102:103]
	v_pk_mul_f32 v[186:187], v[186:187], v[104:105]
	v_pk_mul_f32 v[188:189], v[188:189], v[98:99]
	v_pk_mul_f32 v[190:191], v[190:191], v[100:101]
	v_exp_f32_e32 v184, v184
	v_exp_f32_e32 v185, v185
	v_exp_f32_e32 v186, v186
	v_exp_f32_e32 v187, v187
	v_exp_f32_e32 v188, v188
	v_exp_f32_e32 v189, v189
	v_exp_f32_e32 v190, v190
	v_exp_f32_e32 v191, v191
	v_pk_add_f32 v[184:185], v[184:185], v[178:179]
	v_pk_add_f32 v[186:187], v[186:187], v[178:179]
	v_pk_add_f32 v[188:189], v[188:189], v[178:179]
	v_pk_add_f32 v[190:191], v[190:191], v[178:179]
	v_rcp_f32_e32 v184, v184
	v_rcp_f32_e32 v185, v185
	v_rcp_f32_e32 v186, v186
	v_rcp_f32_e32 v187, v187
	v_rcp_f32_e32 v188, v188
	v_rcp_f32_e32 v189, v189
	v_rcp_f32_e32 v190, v190
	v_rcp_f32_e32 v191, v191
	v_pk_mul_f32 v[102:103], v[102:103], v[184:185]
	v_pk_mul_f32 v[104:105], v[104:105], v[186:187]
	v_pk_mul_f32 v[98:99], v[98:99], v[188:189]
	v_pk_mul_f32 v[100:101], v[100:101], v[190:191]
	v_cvt_pk_bf16_f32 v102, v102, v103
	v_cvt_pk_bf16_f32 v103, v104, v105
	v_cvt_pk_bf16_f32 v104, v98, v99
	v_cvt_pk_bf16_f32 v105, v100, v101
	v_add_u32_e32 v138, 0x8100, v136
	global_store_dwordx4 v138, v[102:105], s[8:9]
	v_pk_mul_f32 v[94:95], v[94:95], v[162:163] op_sel_hi:[1,0]
	v_pk_mul_f32 v[96:97], v[96:97], v[162:163] op_sel_hi:[1,0]
	v_pk_mul_f32 v[90:91], v[90:91], v[162:163] op_sel_hi:[1,0]
	v_pk_mul_f32 v[92:93], v[92:93], v[162:163] op_sel_hi:[1,0]
	v_pk_mul_f32 v[184:185], v[94:95], v[94:95]
	v_pk_mul_f32 v[186:187], v[96:97], v[96:97]
	v_pk_mul_f32 v[188:189], v[90:91], v[90:91]
	v_pk_mul_f32 v[190:191], v[92:93], v[92:93]
	v_pk_fma_f32 v[184:185], v[184:185], v[176:177], v[174:175] op_sel_hi:[1,0,0]
	v_pk_fma_f32 v[186:187], v[186:187], v[176:177], v[174:175] op_sel_hi:[1,0,0]
	v_pk_fma_f32 v[188:189], v[188:189], v[176:177], v[174:175] op_sel_hi:[1,0,0]
	v_pk_fma_f32 v[190:191], v[190:191], v[176:177], v[174:175] op_sel_hi:[1,0,0]
	v_pk_mul_f32 v[184:185], v[184:185], v[94:95]
	v_pk_mul_f32 v[186:187], v[186:187], v[96:97]
	v_pk_mul_f32 v[188:189], v[188:189], v[90:91]
	v_pk_mul_f32 v[190:191], v[190:191], v[92:93]
	v_exp_f32_e32 v184, v184
	v_exp_f32_e32 v185, v185
	v_exp_f32_e32 v186, v186
	v_exp_f32_e32 v187, v187
	v_exp_f32_e32 v188, v188
	v_exp_f32_e32 v189, v189
	v_exp_f32_e32 v190, v190
	v_exp_f32_e32 v191, v191
	v_pk_add_f32 v[184:185], v[184:185], v[178:179]
	v_pk_add_f32 v[186:187], v[186:187], v[178:179]
	v_pk_add_f32 v[188:189], v[188:189], v[178:179]
	v_pk_add_f32 v[190:191], v[190:191], v[178:179]
	v_rcp_f32_e32 v184, v184
	v_rcp_f32_e32 v185, v185
	v_rcp_f32_e32 v186, v186
	v_rcp_f32_e32 v187, v187
	v_rcp_f32_e32 v188, v188
	v_rcp_f32_e32 v189, v189
	v_rcp_f32_e32 v190, v190
	v_rcp_f32_e32 v191, v191
	v_pk_mul_f32 v[94:95], v[94:95], v[184:185]
	v_pk_mul_f32 v[96:97], v[96:97], v[186:187]
	v_pk_mul_f32 v[90:91], v[90:91], v[188:189]
	v_pk_mul_f32 v[92:93], v[92:93], v[190:191]
	v_cvt_pk_bf16_f32 v94, v94, v95
	v_cvt_pk_bf16_f32 v95, v96, v97
	v_cvt_pk_bf16_f32 v96, v90, v91
	v_cvt_pk_bf16_f32 v97, v92, v93
; __device__ __forceinline__ float fgelu(float x) { return x * fsigmoid(1.5957691216057308f * (x + 0.044715f * x * x * x)); }
; __device__ __forceinline__ u32x4 pack8(const f32x4 a, const f32x4 b) { u32x4 w; w.x = cvt_pk_bf16(a[0], a[1]); w.y = cvt_pk_bf16(a[2], a[3]); w.z = cvt_pk_bf16(b[0], b[1]); w.w = cvt_pk_bf16(b[2], b[3]); return w; }
;     __device__ __forceinline__ void operator()(const Acc& acc, const Unit& u, int wr, int wc, int fr, int fq) const {
;     ...
; #pragma unroll
;                 for (int bj = 0; bj < 2; ++bj) {
;                     const size_t o = (size_t)row * DH + col0 + bj * HALF;
;                     f32x4 v0 = acc[ai][bj][m][0] * r, v1 = acc[ai][bj][m][1] * r;
;                     if (seg == 0) { *(u32x4*)(U + o) = pack8(v0, v1); }
;                     else if (seg == 1) { *(f32x4*)(XL + o) = v0; *(f32x4*)(XL + o + 4) = v1; }
;                     else {
; #pragma unroll
;                         for (int j = 0; j < 4; ++j) { v0[j] = fgelu(v0[j]); v1[j] = fgelu(v1[j]); }
;                         *(u32x4*)(GG + o) = pack8(v0, v1);
	v_add_u32_e32 v137, 0x10000, v136
	global_store_dwordx4 v137, v[94:97], s[8:9]
	v_pk_mul_f32 v[86:87], v[86:87], v[162:163] op_sel_hi:[1,0]
	v_pk_mul_f32 v[88:89], v[88:89], v[162:163] op_sel_hi:[1,0]
	v_pk_mul_f32 v[82:83], v[82:83], v[162:163] op_sel_hi:[1,0]
	v_pk_mul_f32 v[84:85], v[84:85], v[162:163] op_sel_hi:[1,0]
	v_pk_mul_f32 v[184:185], v[86:87], v[86:87]
	v_pk_mul_f32 v[186:187], v[88:89], v[88:89]
	v_pk_mul_f32 v[188:189], v[82:83], v[82:83]
	v_pk_mul_f32 v[190:191], v[84:85], v[84:85]
	v_pk_fma_f32 v[184:185], v[184:185], v[176:177], v[174:175] op_sel_hi:[1,0,0]
	v_pk_fma_f32 v[186:187], v[186:187], v[176:177], v[174:175] op_sel_hi:[1,0,0]
	v_pk_fma_f32 v[188:189], v[188:189], v[176:177], v[174:175] op_sel_hi:[1,0,0]
	v_pk_fma_f32 v[190:191], v[190:191], v[176:177], v[174:175] op_sel_hi:[1,0,0]
	v_pk_mul_f32 v[184:185], v[184:185], v[86:87]
	v_pk_mul_f32 v[186:187], v[186:187], v[88:89]
	v_pk_mul_f32 v[188:189], v[188:189], v[82:83]
	v_pk_mul_f32 v[190:191], v[190:191], v[84:85]
	v_exp_f32_e32 v184, v184
	v_exp_f32_e32 v185, v185
	v_exp_f32_e32 v186, v186
	v_exp_f32_e32 v187, v187
	v_exp_f32_e32 v188, v188
	v_exp_f32_e32 v189, v189
	v_exp_f32_e32 v190, v190
	v_exp_f32_e32 v191, v191
	v_pk_add_f32 v[184:185], v[184:185], v[178:179]
	v_pk_add_f32 v[186:187], v[186:187], v[178:179]
	v_pk_add_f32 v[188:189], v[188:189], v[178:179]
	v_pk_add_f32 v[190:191], v[190:191], v[178:179]
	v_rcp_f32_e32 v184, v184
	v_rcp_f32_e32 v185, v185
	v_rcp_f32_e32 v186, v186
	v_rcp_f32_e32 v187, v187
	v_rcp_f32_e32 v188, v188
	v_rcp_f32_e32 v189, v189
	v_rcp_f32_e32 v190, v190
	v_rcp_f32_e32 v191, v191
	v_pk_mul_f32 v[86:87], v[86:87], v[184:185]
	v_pk_mul_f32 v[88:89], v[88:89], v[186:187]
	v_pk_mul_f32 v[82:83], v[82:83], v[188:189]
	v_pk_mul_f32 v[84:85], v[84:85], v[190:191]
	v_cvt_pk_bf16_f32 v86, v86, v87
	v_cvt_pk_bf16_f32 v87, v88, v89
	v_cvt_pk_bf16_f32 v88, v82, v83
	v_cvt_pk_bf16_f32 v89, v84, v85
	v_add_u32_e32 v138, 0x10100, v136
	global_store_dwordx4 v138, v[86:89], s[8:9]
	v_pk_mul_f32 v[70:71], v[70:71], v[164:165] op_sel_hi:[1,0]
	v_pk_mul_f32 v[72:73], v[72:73], v[164:165] op_sel_hi:[1,0]
	v_pk_mul_f32 v[66:67], v[66:67], v[164:165] op_sel_hi:[1,0]
	v_pk_mul_f32 v[68:69], v[68:69], v[164:165] op_sel_hi:[1,0]
	v_pk_mul_f32 v[184:185], v[70:71], v[70:71]
	v_pk_mul_f32 v[186:187], v[72:73], v[72:73]
	v_pk_mul_f32 v[188:189], v[66:67], v[66:67]
	v_pk_mul_f32 v[190:191], v[68:69], v[68:69]
	v_pk_fma_f32 v[184:185], v[184:185], v[176:177], v[174:175] op_sel_hi:[1,0,0]
	v_pk_fma_f32 v[186:187], v[186:187], v[176:177], v[174:175] op_sel_hi:[1,0,0]
	v_pk_fma_f32 v[188:189], v[188:189], v[176:177], v[174:175] op_sel_hi:[1,0,0]
	v_pk_fma_f32 v[190:191], v[190:191], v[176:177], v[174:175] op_sel_hi:[1,0,0]
	v_pk_mul_f32 v[184:185], v[184:185], v[70:71]
	v_pk_mul_f32 v[186:187], v[186:187], v[72:73]
	v_pk_mul_f32 v[188:189], v[188:189], v[66:67]
	v_pk_mul_f32 v[190:191], v[190:191], v[68:69]
	v_exp_f32_e32 v184, v184
	v_exp_f32_e32 v185, v185
	v_exp_f32_e32 v186, v186
	v_exp_f32_e32 v187, v187
	v_exp_f32_e32 v188, v188
	v_exp_f32_e32 v189, v189
	v_exp_f32_e32 v190, v190
	v_exp_f32_e32 v191, v191
	v_pk_add_f32 v[184:185], v[184:185], v[178:179]
	v_pk_add_f32 v[186:187], v[186:187], v[178:179]
	v_pk_add_f32 v[188:189], v[188:189], v[178:179]
	v_pk_add_f32 v[190:191], v[190:191], v[178:179]
	v_rcp_f32_e32 v184, v184
	v_rcp_f32_e32 v185, v185
	v_rcp_f32_e32 v186, v186
	v_rcp_f32_e32 v187, v187
	v_rcp_f32_e32 v188, v188
	v_rcp_f32_e32 v189, v189
	v_rcp_f32_e32 v190, v190
	v_rcp_f32_e32 v191, v191
	v_pk_mul_f32 v[70:71], v[70:71], v[184:185]
	v_pk_mul_f32 v[72:73], v[72:73], v[186:187]
	v_pk_mul_f32 v[66:67], v[66:67], v[188:189]
	v_pk_mul_f32 v[68:69], v[68:69], v[190:191]
	v_cvt_pk_bf16_f32 v70, v70, v71
	v_cvt_pk_bf16_f32 v71, v72, v73
	v_cvt_pk_bf16_f32 v72, v66, v67
	v_cvt_pk_bf16_f32 v73, v68, v69
	v_add_u32_e32 v137, 0x18000, v136
	global_store_dwordx4 v137, v[70:73], s[8:9]
	v_pk_mul_f32 v[54:55], v[54:55], v[164:165] op_sel_hi:[1,0]
	v_pk_mul_f32 v[56:57], v[56:57], v[164:165] op_sel_hi:[1,0]
	v_pk_mul_f32 v[50:51], v[50:51], v[164:165] op_sel_hi:[1,0]
	v_pk_mul_f32 v[52:53], v[52:53], v[164:165] op_sel_hi:[1,0]
	v_pk_mul_f32 v[184:185], v[54:55], v[54:55]
	v_pk_mul_f32 v[186:187], v[56:57], v[56:57]
	v_pk_mul_f32 v[188:189], v[50:51], v[50:51]
	v_pk_mul_f32 v[190:191], v[52:53], v[52:53]
	v_pk_fma_f32 v[184:185], v[184:185], v[176:177], v[174:175] op_sel_hi:[1,0,0]
	v_pk_fma_f32 v[186:187], v[186:187], v[176:177], v[174:175] op_sel_hi:[1,0,0]
	v_pk_fma_f32 v[188:189], v[188:189], v[176:177], v[174:175] op_sel_hi:[1,0,0]
	v_pk_fma_f32 v[190:191], v[190:191], v[176:177], v[174:175] op_sel_hi:[1,0,0]
	v_pk_mul_f32 v[184:185], v[184:185], v[54:55]
	v_pk_mul_f32 v[186:187], v[186:187], v[56:57]
	v_pk_mul_f32 v[188:189], v[188:189], v[50:51]
	v_pk_mul_f32 v[190:191], v[190:191], v[52:53]
	v_exp_f32_e32 v184, v184
	v_exp_f32_e32 v185, v185
	v_exp_f32_e32 v186, v186
	v_exp_f32_e32 v187, v187
	v_exp_f32_e32 v188, v188
	v_exp_f32_e32 v189, v189
	v_exp_f32_e32 v190, v190
	v_exp_f32_e32 v191, v191
	v_pk_add_f32 v[184:185], v[184:185], v[178:179]
	v_pk_add_f32 v[186:187], v[186:187], v[178:179]
	v_pk_add_f32 v[188:189], v[188:189], v[178:179]
	v_pk_add_f32 v[190:191], v[190:191], v[178:179]
	v_rcp_f32_e32 v184, v184
	v_rcp_f32_e32 v185, v185
	v_rcp_f32_e32 v186, v186
	v_rcp_f32_e32 v187, v187
	v_rcp_f32_e32 v188, v188
	v_rcp_f32_e32 v189, v189
	v_rcp_f32_e32 v190, v190
	v_rcp_f32_e32 v191, v191
	v_pk_mul_f32 v[54:55], v[54:55], v[184:185]
	v_pk_mul_f32 v[56:57], v[56:57], v[186:187]
	v_pk_mul_f32 v[50:51], v[50:51], v[188:189]
; __device__ __forceinline__ float fgelu(float x) { return x * fsigmoid(1.5957691216057308f * (x + 0.044715f * x * x * x)); }
; __device__ __forceinline__ u32x4 pack8(const f32x4 a, const f32x4 b) { u32x4 w; w.x = cvt_pk_bf16(a[0], a[1]); w.y = cvt_pk_bf16(a[2], a[3]); w.z = cvt_pk_bf16(b[0], b[1]); w.w = cvt_pk_bf16(b[2], b[3]); return w; }
;     __device__ __forceinline__ void operator()(const Acc& acc, const Unit& u, int wr, int wc, int fr, int fq) const {
;     ...
; #pragma unroll
;                 for (int bj = 0; bj < 2; ++bj) {
;                     const size_t o = (size_t)row * DH + col0 + bj * HALF;
;                     f32x4 v0 = acc[ai][bj][m][0] * r, v1 = acc[ai][bj][m][1] * r;
;                     if (seg == 0) { *(u32x4*)(U + o) = pack8(v0, v1); }
;                     else if (seg == 1) { *(f32x4*)(XL + o) = v0; *(f32x4*)(XL + o + 4) = v1; }
;                     else {
; #pragma unroll
;                         for (int j = 0; j < 4; ++j) { v0[j] = fgelu(v0[j]); v1[j] = fgelu(v1[j]); }
;                         *(u32x4*)(GG + o) = pack8(v0, v1);
	v_pk_mul_f32 v[52:53], v[52:53], v[190:191]
	v_cvt_pk_bf16_f32 v54, v54, v55
	v_cvt_pk_bf16_f32 v55, v56, v57
	v_cvt_pk_bf16_f32 v56, v50, v51
	v_cvt_pk_bf16_f32 v57, v52, v53
	v_add_u32_e32 v138, 0x18100, v136
	global_store_dwordx4 v138, v[54:57], s[8:9]
	v_pk_mul_f32 v[78:79], v[78:79], v[166:167] op_sel_hi:[1,0]
	v_pk_mul_f32 v[80:81], v[80:81], v[166:167] op_sel_hi:[1,0]
	v_pk_mul_f32 v[74:75], v[74:75], v[166:167] op_sel_hi:[1,0]
	v_pk_mul_f32 v[76:77], v[76:77], v[166:167] op_sel_hi:[1,0]
	v_pk_mul_f32 v[184:185], v[78:79], v[78:79]
	v_pk_mul_f32 v[186:187], v[80:81], v[80:81]
	v_pk_mul_f32 v[188:189], v[74:75], v[74:75]
	v_pk_mul_f32 v[190:191], v[76:77], v[76:77]
	v_pk_fma_f32 v[184:185], v[184:185], v[176:177], v[174:175] op_sel_hi:[1,0,0]
	v_pk_fma_f32 v[186:187], v[186:187], v[176:177], v[174:175] op_sel_hi:[1,0,0]
	v_pk_fma_f32 v[188:189], v[188:189], v[176:177], v[174:175] op_sel_hi:[1,0,0]
	v_pk_fma_f32 v[190:191], v[190:191], v[176:177], v[174:175] op_sel_hi:[1,0,0]
	v_pk_mul_f32 v[184:185], v[184:185], v[78:79]
	v_pk_mul_f32 v[186:187], v[186:187], v[80:81]
	v_pk_mul_f32 v[188:189], v[188:189], v[74:75]
	v_pk_mul_f32 v[190:191], v[190:191], v[76:77]
	v_exp_f32_e32 v184, v184
	v_exp_f32_e32 v185, v185
	v_exp_f32_e32 v186, v186
	v_exp_f32_e32 v187, v187
	v_exp_f32_e32 v188, v188
	v_exp_f32_e32 v189, v189
	v_exp_f32_e32 v190, v190
	v_exp_f32_e32 v191, v191
	v_pk_add_f32 v[184:185], v[184:185], v[178:179]
	v_pk_add_f32 v[186:187], v[186:187], v[178:179]
	v_pk_add_f32 v[188:189], v[188:189], v[178:179]
	v_pk_add_f32 v[190:191], v[190:191], v[178:179]
	v_rcp_f32_e32 v184, v184
	v_rcp_f32_e32 v185, v185
	v_rcp_f32_e32 v186, v186
	v_rcp_f32_e32 v187, v187
	v_rcp_f32_e32 v188, v188
	v_rcp_f32_e32 v189, v189
	v_rcp_f32_e32 v190, v190
	v_rcp_f32_e32 v191, v191
	v_pk_mul_f32 v[78:79], v[78:79], v[184:185]
	v_pk_mul_f32 v[80:81], v[80:81], v[186:187]
	v_pk_mul_f32 v[74:75], v[74:75], v[188:189]
	v_pk_mul_f32 v[76:77], v[76:77], v[190:191]
	v_cvt_pk_bf16_f32 v78, v78, v79
	v_cvt_pk_bf16_f32 v79, v80, v81
	v_cvt_pk_bf16_f32 v80, v74, v75
	v_cvt_pk_bf16_f32 v81, v76, v77
	v_add_u32_e32 v137, 0x40000, v136
	global_store_dwordx4 v137, v[78:81], s[8:9]
	v_pk_mul_f32 v[62:63], v[62:63], v[166:167] op_sel_hi:[1,0]
	v_pk_mul_f32 v[64:65], v[64:65], v[166:167] op_sel_hi:[1,0]
	v_pk_mul_f32 v[58:59], v[58:59], v[166:167] op_sel_hi:[1,0]
	v_pk_mul_f32 v[60:61], v[60:61], v[166:167] op_sel_hi:[1,0]
	v_pk_mul_f32 v[184:185], v[62:63], v[62:63]
	v_pk_mul_f32 v[186:187], v[64:65], v[64:65]
	v_pk_mul_f32 v[188:189], v[58:59], v[58:59]
	v_pk_mul_f32 v[190:191], v[60:61], v[60:61]
	v_pk_fma_f32 v[184:185], v[184:185], v[176:177], v[174:175] op_sel_hi:[1,0,0]
	v_pk_fma_f32 v[186:187], v[186:187], v[176:177], v[174:175] op_sel_hi:[1,0,0]
	v_pk_fma_f32 v[188:189], v[188:189], v[176:177], v[174:175] op_sel_hi:[1,0,0]
	v_pk_fma_f32 v[190:191], v[190:191], v[176:177], v[174:175] op_sel_hi:[1,0,0]
	v_pk_mul_f32 v[184:185], v[184:185], v[62:63]
	v_pk_mul_f32 v[186:187], v[186:187], v[64:65]
	v_pk_mul_f32 v[188:189], v[188:189], v[58:59]
	v_pk_mul_f32 v[190:191], v[190:191], v[60:61]
	v_exp_f32_e32 v184, v184
	v_exp_f32_e32 v185, v185
	v_exp_f32_e32 v186, v186
	v_exp_f32_e32 v187, v187
	v_exp_f32_e32 v188, v188
	v_exp_f32_e32 v189, v189
	v_exp_f32_e32 v190, v190
	v_exp_f32_e32 v191, v191
	v_pk_add_f32 v[184:185], v[184:185], v[178:179]
	v_pk_add_f32 v[186:187], v[186:187], v[178:179]
	v_pk_add_f32 v[188:189], v[188:189], v[178:179]
	v_pk_add_f32 v[190:191], v[190:191], v[178:179]
	v_rcp_f32_e32 v184, v184
	v_rcp_f32_e32 v185, v185
	v_rcp_f32_e32 v186, v186
	v_rcp_f32_e32 v187, v187
	v_rcp_f32_e32 v188, v188
	v_rcp_f32_e32 v189, v189
	v_rcp_f32_e32 v190, v190
	v_rcp_f32_e32 v191, v191
	v_pk_mul_f32 v[62:63], v[62:63], v[184:185]
	v_pk_mul_f32 v[64:65], v[64:65], v[186:187]
	v_pk_mul_f32 v[58:59], v[58:59], v[188:189]
	v_pk_mul_f32 v[60:61], v[60:61], v[190:191]
	v_cvt_pk_bf16_f32 v62, v62, v63
	v_cvt_pk_bf16_f32 v63, v64, v65
	v_cvt_pk_bf16_f32 v64, v58, v59
	v_cvt_pk_bf16_f32 v65, v60, v61
	v_add_u32_e32 v138, 0x40100, v136
	global_store_dwordx4 v138, v[62:65], s[8:9]
	v_pk_mul_f32 v[46:47], v[46:47], v[168:169] op_sel_hi:[1,0]
	v_pk_mul_f32 v[48:49], v[48:49], v[168:169] op_sel_hi:[1,0]
	v_pk_mul_f32 v[42:43], v[42:43], v[168:169] op_sel_hi:[1,0]
	v_pk_mul_f32 v[44:45], v[44:45], v[168:169] op_sel_hi:[1,0]
	v_pk_mul_f32 v[184:185], v[46:47], v[46:47]
	v_pk_mul_f32 v[186:187], v[48:49], v[48:49]
	v_pk_mul_f32 v[188:189], v[42:43], v[42:43]
	v_pk_mul_f32 v[190:191], v[44:45], v[44:45]
	v_pk_fma_f32 v[184:185], v[184:185], v[176:177], v[174:175] op_sel_hi:[1,0,0]
	v_pk_fma_f32 v[186:187], v[186:187], v[176:177], v[174:175] op_sel_hi:[1,0,0]
	v_pk_fma_f32 v[188:189], v[188:189], v[176:177], v[174:175] op_sel_hi:[1,0,0]
	v_pk_fma_f32 v[190:191], v[190:191], v[176:177], v[174:175] op_sel_hi:[1,0,0]
	v_pk_mul_f32 v[184:185], v[184:185], v[46:47]
	v_pk_mul_f32 v[186:187], v[186:187], v[48:49]
	v_pk_mul_f32 v[188:189], v[188:189], v[42:43]
	v_pk_mul_f32 v[190:191], v[190:191], v[44:45]
	v_exp_f32_e32 v184, v184
	v_exp_f32_e32 v185, v185
	v_exp_f32_e32 v186, v186
	v_exp_f32_e32 v187, v187
	v_exp_f32_e32 v188, v188
	v_exp_f32_e32 v189, v189
	v_exp_f32_e32 v190, v190
	v_exp_f32_e32 v191, v191
	v_pk_add_f32 v[184:185], v[184:185], v[178:179]
	v_pk_add_f32 v[186:187], v[186:187], v[178:179]
	v_pk_add_f32 v[188:189], v[188:189], v[178:179]
	v_pk_add_f32 v[190:191], v[190:191], v[178:179]
	v_rcp_f32_e32 v184, v184
	v_rcp_f32_e32 v185, v185
	v_rcp_f32_e32 v186, v186
	v_rcp_f32_e32 v187, v187
	v_rcp_f32_e32 v188, v188
	v_rcp_f32_e32 v189, v189
	v_rcp_f32_e32 v190, v190
; __device__ __forceinline__ float fgelu(float x) { return x * fsigmoid(1.5957691216057308f * (x + 0.044715f * x * x * x)); }
; __device__ __forceinline__ u32x4 pack8(const f32x4 a, const f32x4 b) { u32x4 w; w.x = cvt_pk_bf16(a[0], a[1]); w.y = cvt_pk_bf16(a[2], a[3]); w.z = cvt_pk_bf16(b[0], b[1]); w.w = cvt_pk_bf16(b[2], b[3]); return w; }
;     __device__ __forceinline__ void operator()(const Acc& acc, const Unit& u, int wr, int wc, int fr, int fq) const {
;     ...
; #pragma unroll
;                 for (int bj = 0; bj < 2; ++bj) {
;                     const size_t o = (size_t)row * DH + col0 + bj * HALF;
;                     f32x4 v0 = acc[ai][bj][m][0] * r, v1 = acc[ai][bj][m][1] * r;
;                     if (seg == 0) { *(u32x4*)(U + o) = pack8(v0, v1); }
;                     else if (seg == 1) { *(f32x4*)(XL + o) = v0; *(f32x4*)(XL + o + 4) = v1; }
;                     else {
; #pragma unroll
;                         for (int j = 0; j < 4; ++j) { v0[j] = fgelu(v0[j]); v1[j] = fgelu(v1[j]); }
;                         *(u32x4*)(GG + o) = pack8(v0, v1);
	v_rcp_f32_e32 v191, v191
	v_pk_mul_f32 v[46:47], v[46:47], v[184:185]
	v_pk_mul_f32 v[48:49], v[48:49], v[186:187]
	v_pk_mul_f32 v[42:43], v[42:43], v[188:189]
	v_pk_mul_f32 v[44:45], v[44:45], v[190:191]
	v_cvt_pk_bf16_f32 v46, v46, v47
	v_cvt_pk_bf16_f32 v47, v48, v49
	v_cvt_pk_bf16_f32 v48, v42, v43
	v_cvt_pk_bf16_f32 v49, v44, v45
	v_add_u32_e32 v137, 0x48000, v136
	global_store_dwordx4 v137, v[46:49], s[8:9]
	v_pk_mul_f32 v[38:39], v[38:39], v[168:169] op_sel_hi:[1,0]
	v_pk_mul_f32 v[40:41], v[40:41], v[168:169] op_sel_hi:[1,0]
	v_pk_mul_f32 v[34:35], v[34:35], v[168:169] op_sel_hi:[1,0]
	v_pk_mul_f32 v[36:37], v[36:37], v[168:169] op_sel_hi:[1,0]
	v_pk_mul_f32 v[184:185], v[38:39], v[38:39]
	v_pk_mul_f32 v[186:187], v[40:41], v[40:41]
	v_pk_mul_f32 v[188:189], v[34:35], v[34:35]
	v_pk_mul_f32 v[190:191], v[36:37], v[36:37]
	v_pk_fma_f32 v[184:185], v[184:185], v[176:177], v[174:175] op_sel_hi:[1,0,0]
	v_pk_fma_f32 v[186:187], v[186:187], v[176:177], v[174:175] op_sel_hi:[1,0,0]
	v_pk_fma_f32 v[188:189], v[188:189], v[176:177], v[174:175] op_sel_hi:[1,0,0]
	v_pk_fma_f32 v[190:191], v[190:191], v[176:177], v[174:175] op_sel_hi:[1,0,0]
	v_pk_mul_f32 v[184:185], v[184:185], v[38:39]
	v_pk_mul_f32 v[186:187], v[186:187], v[40:41]
	v_pk_mul_f32 v[188:189], v[188:189], v[34:35]
	v_pk_mul_f32 v[190:191], v[190:191], v[36:37]
	v_exp_f32_e32 v184, v184
	v_exp_f32_e32 v185, v185
	v_exp_f32_e32 v186, v186
	v_exp_f32_e32 v187, v187
	v_exp_f32_e32 v188, v188
	v_exp_f32_e32 v189, v189
	v_exp_f32_e32 v190, v190
	v_exp_f32_e32 v191, v191
	v_pk_add_f32 v[184:185], v[184:185], v[178:179]
	v_pk_add_f32 v[186:187], v[186:187], v[178:179]
	v_pk_add_f32 v[188:189], v[188:189], v[178:179]
	v_pk_add_f32 v[190:191], v[190:191], v[178:179]
	v_rcp_f32_e32 v184, v184
	v_rcp_f32_e32 v185, v185
	v_rcp_f32_e32 v186, v186
	v_rcp_f32_e32 v187, v187
	v_rcp_f32_e32 v188, v188
	v_rcp_f32_e32 v189, v189
	v_rcp_f32_e32 v190, v190
	v_rcp_f32_e32 v191, v191
	v_pk_mul_f32 v[38:39], v[38:39], v[184:185]
	v_pk_mul_f32 v[40:41], v[40:41], v[186:187]
	v_pk_mul_f32 v[34:35], v[34:35], v[188:189]
	v_pk_mul_f32 v[36:37], v[36:37], v[190:191]
	v_cvt_pk_bf16_f32 v38, v38, v39
	v_cvt_pk_bf16_f32 v39, v40, v41
	v_cvt_pk_bf16_f32 v40, v34, v35
	v_cvt_pk_bf16_f32 v41, v36, v37
	v_add_u32_e32 v138, 0x48100, v136
	global_store_dwordx4 v138, v[38:41], s[8:9]
	v_pk_mul_f32 v[30:31], v[30:31], v[170:171] op_sel_hi:[1,0]
	v_pk_mul_f32 v[32:33], v[32:33], v[170:171] op_sel_hi:[1,0]
	v_pk_mul_f32 v[26:27], v[26:27], v[170:171] op_sel_hi:[1,0]
	v_pk_mul_f32 v[28:29], v[28:29], v[170:171] op_sel_hi:[1,0]
	v_pk_mul_f32 v[184:185], v[30:31], v[30:31]
	v_pk_mul_f32 v[186:187], v[32:33], v[32:33]
	v_pk_mul_f32 v[188:189], v[26:27], v[26:27]
	v_pk_mul_f32 v[190:191], v[28:29], v[28:29]
	v_pk_fma_f32 v[184:185], v[184:185], v[176:177], v[174:175] op_sel_hi:[1,0,0]
	v_pk_fma_f32 v[186:187], v[186:187], v[176:177], v[174:175] op_sel_hi:[1,0,0]
	v_pk_fma_f32 v[188:189], v[188:189], v[176:177], v[174:175] op_sel_hi:[1,0,0]
	v_pk_fma_f32 v[190:191], v[190:191], v[176:177], v[174:175] op_sel_hi:[1,0,0]
	v_pk_mul_f32 v[184:185], v[184:185], v[30:31]
	v_pk_mul_f32 v[186:187], v[186:187], v[32:33]
	v_pk_mul_f32 v[188:189], v[188:189], v[26:27]
	v_pk_mul_f32 v[190:191], v[190:191], v[28:29]
	v_exp_f32_e32 v184, v184
	v_exp_f32_e32 v185, v185
	v_exp_f32_e32 v186, v186
	v_exp_f32_e32 v187, v187
	v_exp_f32_e32 v188, v188
	v_exp_f32_e32 v189, v189
	v_exp_f32_e32 v190, v190
	v_exp_f32_e32 v191, v191
	v_pk_add_f32 v[184:185], v[184:185], v[178:179]
	v_pk_add_f32 v[186:187], v[186:187], v[178:179]
	v_pk_add_f32 v[188:189], v[188:189], v[178:179]
	v_pk_add_f32 v[190:191], v[190:191], v[178:179]
	v_rcp_f32_e32 v184, v184
	v_rcp_f32_e32 v185, v185
	v_rcp_f32_e32 v186, v186
	v_rcp_f32_e32 v187, v187
	v_rcp_f32_e32 v188, v188
	v_rcp_f32_e32 v189, v189
	v_rcp_f32_e32 v190, v190
	v_rcp_f32_e32 v191, v191
	v_pk_mul_f32 v[30:31], v[30:31], v[184:185]
	v_pk_mul_f32 v[32:33], v[32:33], v[186:187]
	v_pk_mul_f32 v[26:27], v[26:27], v[188:189]
	v_pk_mul_f32 v[28:29], v[28:29], v[190:191]
	v_cvt_pk_bf16_f32 v30, v30, v31
	v_cvt_pk_bf16_f32 v31, v32, v33
	v_cvt_pk_bf16_f32 v32, v26, v27
	v_cvt_pk_bf16_f32 v33, v28, v29
	v_add_u32_e32 v137, 0x50000, v136
	global_store_dwordx4 v137, v[30:33], s[8:9]
	v_pk_mul_f32 v[22:23], v[22:23], v[170:171] op_sel_hi:[1,0]
	v_pk_mul_f32 v[24:25], v[24:25], v[170:171] op_sel_hi:[1,0]
	v_pk_mul_f32 v[18:19], v[18:19], v[170:171] op_sel_hi:[1,0]
	v_pk_mul_f32 v[20:21], v[20:21], v[170:171] op_sel_hi:[1,0]
	v_pk_mul_f32 v[184:185], v[22:23], v[22:23]
	v_pk_mul_f32 v[186:187], v[24:25], v[24:25]
	v_pk_mul_f32 v[188:189], v[18:19], v[18:19]
	v_pk_mul_f32 v[190:191], v[20:21], v[20:21]
	v_pk_fma_f32 v[184:185], v[184:185], v[176:177], v[174:175] op_sel_hi:[1,0,0]
	v_pk_fma_f32 v[186:187], v[186:187], v[176:177], v[174:175] op_sel_hi:[1,0,0]
	v_pk_fma_f32 v[188:189], v[188:189], v[176:177], v[174:175] op_sel_hi:[1,0,0]
	v_pk_fma_f32 v[190:191], v[190:191], v[176:177], v[174:175] op_sel_hi:[1,0,0]
	v_pk_mul_f32 v[184:185], v[184:185], v[22:23]
	v_pk_mul_f32 v[186:187], v[186:187], v[24:25]
	v_pk_mul_f32 v[188:189], v[188:189], v[18:19]
	v_pk_mul_f32 v[190:191], v[190:191], v[20:21]
	v_exp_f32_e32 v184, v184
	v_exp_f32_e32 v185, v185
	v_exp_f32_e32 v186, v186
	v_exp_f32_e32 v187, v187
	v_exp_f32_e32 v188, v188
	v_exp_f32_e32 v189, v189
	v_exp_f32_e32 v190, v190
	v_exp_f32_e32 v191, v191
	v_pk_add_f32 v[184:185], v[184:185], v[178:179]
	v_pk_add_f32 v[186:187], v[186:187], v[178:179]
	v_pk_add_f32 v[188:189], v[188:189], v[178:179]
	v_pk_add_f32 v[190:191], v[190:191], v[178:179]
	v_rcp_f32_e32 v184, v184
; __device__ __forceinline__ float fgelu(float x) { return x * fsigmoid(1.5957691216057308f * (x + 0.044715f * x * x * x)); }
; __device__ __forceinline__ u32x4 pack8(const f32x4 a, const f32x4 b) { u32x4 w; w.x = cvt_pk_bf16(a[0], a[1]); w.y = cvt_pk_bf16(a[2], a[3]); w.z = cvt_pk_bf16(b[0], b[1]); w.w = cvt_pk_bf16(b[2], b[3]); return w; }
;     __device__ __forceinline__ void operator()(const Acc& acc, const Unit& u, int wr, int wc, int fr, int fq) const {
;     ...
; #pragma unroll
;                 for (int bj = 0; bj < 2; ++bj) {
;                     const size_t o = (size_t)row * DH + col0 + bj * HALF;
;                     f32x4 v0 = acc[ai][bj][m][0] * r, v1 = acc[ai][bj][m][1] * r;
;                     if (seg == 0) { *(u32x4*)(U + o) = pack8(v0, v1); }
;                     else if (seg == 1) { *(f32x4*)(XL + o) = v0; *(f32x4*)(XL + o + 4) = v1; }
;                     else {
; #pragma unroll
;                         for (int j = 0; j < 4; ++j) { v0[j] = fgelu(v0[j]); v1[j] = fgelu(v1[j]); }
;                         *(u32x4*)(GG + o) = pack8(v0, v1);
	v_rcp_f32_e32 v185, v185
	v_rcp_f32_e32 v186, v186
	v_rcp_f32_e32 v187, v187
	v_rcp_f32_e32 v188, v188
	v_rcp_f32_e32 v189, v189
	v_rcp_f32_e32 v190, v190
	v_rcp_f32_e32 v191, v191
	v_pk_mul_f32 v[22:23], v[22:23], v[184:185]
	v_pk_mul_f32 v[24:25], v[24:25], v[186:187]
	v_pk_mul_f32 v[18:19], v[18:19], v[188:189]
	v_pk_mul_f32 v[20:21], v[20:21], v[190:191]
	v_cvt_pk_bf16_f32 v22, v22, v23
	v_cvt_pk_bf16_f32 v23, v24, v25
	v_cvt_pk_bf16_f32 v24, v18, v19
	v_cvt_pk_bf16_f32 v25, v20, v21
	v_add_u32_e32 v138, 0x50100, v136
	global_store_dwordx4 v138, v[22:25], s[8:9]
	v_pk_mul_f32 v[14:15], v[14:15], v[172:173] op_sel_hi:[1,0]
	v_pk_mul_f32 v[16:17], v[16:17], v[172:173] op_sel_hi:[1,0]
	v_pk_mul_f32 v[10:11], v[10:11], v[172:173] op_sel_hi:[1,0]
	v_pk_mul_f32 v[12:13], v[12:13], v[172:173] op_sel_hi:[1,0]
	v_pk_mul_f32 v[184:185], v[14:15], v[14:15]
	v_pk_mul_f32 v[186:187], v[16:17], v[16:17]
	v_pk_mul_f32 v[188:189], v[10:11], v[10:11]
	v_pk_mul_f32 v[190:191], v[12:13], v[12:13]
	v_pk_fma_f32 v[184:185], v[184:185], v[176:177], v[174:175] op_sel_hi:[1,0,0]
	v_pk_fma_f32 v[186:187], v[186:187], v[176:177], v[174:175] op_sel_hi:[1,0,0]
	v_pk_fma_f32 v[188:189], v[188:189], v[176:177], v[174:175] op_sel_hi:[1,0,0]
	v_pk_fma_f32 v[190:191], v[190:191], v[176:177], v[174:175] op_sel_hi:[1,0,0]
	v_pk_mul_f32 v[184:185], v[184:185], v[14:15]
	v_pk_mul_f32 v[186:187], v[186:187], v[16:17]
	v_pk_mul_f32 v[188:189], v[188:189], v[10:11]
	v_pk_mul_f32 v[190:191], v[190:191], v[12:13]
	v_exp_f32_e32 v184, v184
	v_exp_f32_e32 v185, v185
	v_exp_f32_e32 v186, v186
	v_exp_f32_e32 v187, v187
	v_exp_f32_e32 v188, v188
	v_exp_f32_e32 v189, v189
	v_exp_f32_e32 v190, v190
	v_exp_f32_e32 v191, v191
	v_pk_add_f32 v[184:185], v[184:185], v[178:179]
	v_pk_add_f32 v[186:187], v[186:187], v[178:179]
	v_pk_add_f32 v[188:189], v[188:189], v[178:179]
	v_pk_add_f32 v[190:191], v[190:191], v[178:179]
	v_rcp_f32_e32 v184, v184
	v_rcp_f32_e32 v185, v185
	v_rcp_f32_e32 v186, v186
	v_rcp_f32_e32 v187, v187
	v_rcp_f32_e32 v188, v188
	v_rcp_f32_e32 v189, v189
	v_rcp_f32_e32 v190, v190
	v_rcp_f32_e32 v191, v191
	v_pk_mul_f32 v[14:15], v[14:15], v[184:185]
	v_pk_mul_f32 v[16:17], v[16:17], v[186:187]
	v_pk_mul_f32 v[10:11], v[10:11], v[188:189]
	v_pk_mul_f32 v[12:13], v[12:13], v[190:191]
	v_cvt_pk_bf16_f32 v14, v14, v15
	v_cvt_pk_bf16_f32 v15, v16, v17
	v_cvt_pk_bf16_f32 v16, v10, v11
	v_cvt_pk_bf16_f32 v17, v12, v13
	v_add_u32_e32 v137, 0x58000, v136
	global_store_dwordx4 v137, v[14:17], s[8:9]
	v_pk_mul_f32 v[6:7], v[6:7], v[172:173] op_sel_hi:[1,0]
	v_pk_mul_f32 v[8:9], v[8:9], v[172:173] op_sel_hi:[1,0]
	v_pk_mul_f32 v[2:3], v[2:3], v[172:173] op_sel_hi:[1,0]
	v_pk_mul_f32 v[4:5], v[4:5], v[172:173] op_sel_hi:[1,0]
	v_pk_mul_f32 v[184:185], v[6:7], v[6:7]
	v_pk_mul_f32 v[186:187], v[8:9], v[8:9]
	v_pk_mul_f32 v[188:189], v[2:3], v[2:3]
	v_pk_mul_f32 v[190:191], v[4:5], v[4:5]
	v_pk_fma_f32 v[184:185], v[184:185], v[176:177], v[174:175] op_sel_hi:[1,0,0]
	v_pk_fma_f32 v[186:187], v[186:187], v[176:177], v[174:175] op_sel_hi:[1,0,0]
	v_pk_fma_f32 v[188:189], v[188:189], v[176:177], v[174:175] op_sel_hi:[1,0,0]
	v_pk_fma_f32 v[190:191], v[190:191], v[176:177], v[174:175] op_sel_hi:[1,0,0]
	v_pk_mul_f32 v[184:185], v[184:185], v[6:7]
	v_pk_mul_f32 v[186:187], v[186:187], v[8:9]
	v_pk_mul_f32 v[188:189], v[188:189], v[2:3]
	v_pk_mul_f32 v[190:191], v[190:191], v[4:5]
	v_exp_f32_e32 v184, v184
	v_exp_f32_e32 v185, v185
	v_exp_f32_e32 v186, v186
	v_exp_f32_e32 v187, v187
	v_exp_f32_e32 v188, v188
	v_exp_f32_e32 v189, v189
	v_exp_f32_e32 v190, v190
	v_exp_f32_e32 v191, v191
	v_pk_add_f32 v[184:185], v[184:185], v[178:179]
	v_pk_add_f32 v[186:187], v[186:187], v[178:179]
	v_pk_add_f32 v[188:189], v[188:189], v[178:179]
	v_pk_add_f32 v[190:191], v[190:191], v[178:179]
	v_rcp_f32_e32 v184, v184
	v_rcp_f32_e32 v185, v185
	v_rcp_f32_e32 v186, v186
	v_rcp_f32_e32 v187, v187
	v_rcp_f32_e32 v188, v188
	v_rcp_f32_e32 v189, v189
	v_rcp_f32_e32 v190, v190
	v_rcp_f32_e32 v191, v191
	v_pk_mul_f32 v[6:7], v[6:7], v[184:185]
	v_pk_mul_f32 v[8:9], v[8:9], v[186:187]
	v_pk_mul_f32 v[2:3], v[2:3], v[188:189]
	v_pk_mul_f32 v[4:5], v[4:5], v[190:191]
	v_cvt_pk_bf16_f32 v6, v6, v7
	v_cvt_pk_bf16_f32 v7, v8, v9
	v_cvt_pk_bf16_f32 v8, v2, v3
	v_cvt_pk_bf16_f32 v9, v4, v5
	v_add_u32_e32 v138, 0x58100, v136
	global_store_dwordx4 v138, v[6:9], s[8:9]
	s_branch .Lep3_done
; __device__ __forceinline__ u32x4 pack8(const f32x4 a, const f32x4 b) { u32x4 w; w.x = cvt_pk_bf16(a[0], a[1]); w.y = cvt_pk_bf16(a[2], a[3]); w.z = cvt_pk_bf16(b[0], b[1]); w.w = cvt_pk_bf16(b[2], b[3]); return w; }
;     __device__ __forceinline__ void operator()(const Acc& acc, const Unit& u, int wr, int wc, int fr, int fq) const {
;     ...
; #pragma unroll
;                 for (int bj = 0; bj < 2; ++bj) {
;                     const size_t o = (size_t)row * DH + col0 + bj * HALF;
;                     f32x4 v0 = acc[ai][bj][m][0] * r, v1 = acc[ai][bj][m][1] * r;
;                     if (seg == 0) { *(u32x4*)(U + o) = pack8(v0, v1); }
.Lep3_u:
	v_readlane_b32 s8, v254, 40
	v_readlane_b32 s9, v254, 41
	v_lshlrev_b32_e32 v136, 1, v135
	v_pk_mul_f32 v[126:127], v[126:127], v[158:159] op_sel_hi:[1,0]
	v_pk_mul_f32 v[128:129], v[128:129], v[158:159] op_sel_hi:[1,0]
	v_pk_mul_f32 v[122:123], v[122:123], v[158:159] op_sel_hi:[1,0]
	v_pk_mul_f32 v[124:125], v[124:125], v[158:159] op_sel_hi:[1,0]
	v_cvt_pk_bf16_f32 v126, v126, v127
	v_cvt_pk_bf16_f32 v127, v128, v129
	v_cvt_pk_bf16_f32 v128, v122, v123
	v_cvt_pk_bf16_f32 v129, v124, v125
	global_store_dwordx4 v136, v[126:129], s[8:9]
	v_pk_mul_f32 v[118:119], v[118:119], v[158:159] op_sel_hi:[1,0]
	v_pk_mul_f32 v[120:121], v[120:121], v[158:159] op_sel_hi:[1,0]
	v_pk_mul_f32 v[114:115], v[114:115], v[158:159] op_sel_hi:[1,0]
	v_pk_mul_f32 v[116:117], v[116:117], v[158:159] op_sel_hi:[1,0]
	v_cvt_pk_bf16_f32 v118, v118, v119
	v_cvt_pk_bf16_f32 v119, v120, v121
	v_cvt_pk_bf16_f32 v120, v114, v115
	v_cvt_pk_bf16_f32 v121, v116, v117
	v_add_u32_e32 v138, 0x100, v136
	global_store_dwordx4 v138, v[118:121], s[8:9]
	v_pk_mul_f32 v[110:111], v[110:111], v[160:161] op_sel_hi:[1,0]
	v_pk_mul_f32 v[112:113], v[112:113], v[160:161] op_sel_hi:[1,0]
	v_pk_mul_f32 v[106:107], v[106:107], v[160:161] op_sel_hi:[1,0]
	v_pk_mul_f32 v[108:109], v[108:109], v[160:161] op_sel_hi:[1,0]
	v_cvt_pk_bf16_f32 v110, v110, v111
	v_cvt_pk_bf16_f32 v111, v112, v113
	v_cvt_pk_bf16_f32 v112, v106, v107
	v_cvt_pk_bf16_f32 v113, v108, v109
	v_add_u32_e32 v137, 0x8000, v136
	global_store_dwordx4 v137, v[110:113], s[8:9]
	v_pk_mul_f32 v[102:103], v[102:103], v[160:161] op_sel_hi:[1,0]
	v_pk_mul_f32 v[104:105], v[104:105], v[160:161] op_sel_hi:[1,0]
	v_pk_mul_f32 v[98:99], v[98:99], v[160:161] op_sel_hi:[1,0]
	v_pk_mul_f32 v[100:101], v[100:101], v[160:161] op_sel_hi:[1,0]
	v_cvt_pk_bf16_f32 v102, v102, v103
	v_cvt_pk_bf16_f32 v103, v104, v105
	v_cvt_pk_bf16_f32 v104, v98, v99
	v_cvt_pk_bf16_f32 v105, v100, v101
	v_add_u32_e32 v138, 0x8100, v136
	global_store_dwordx4 v138, v[102:105], s[8:9]
	v_pk_mul_f32 v[94:95], v[94:95], v[162:163] op_sel_hi:[1,0]
	v_pk_mul_f32 v[96:97], v[96:97], v[162:163] op_sel_hi:[1,0]
	v_pk_mul_f32 v[90:91], v[90:91], v[162:163] op_sel_hi:[1,0]
	v_pk_mul_f32 v[92:93], v[92:93], v[162:163] op_sel_hi:[1,0]
	v_cvt_pk_bf16_f32 v94, v94, v95
	v_cvt_pk_bf16_f32 v95, v96, v97
	v_cvt_pk_bf16_f32 v96, v90, v91
	v_cvt_pk_bf16_f32 v97, v92, v93
	v_add_u32_e32 v137, 0x10000, v136
	global_store_dwordx4 v137, v[94:97], s[8:9]
	v_pk_mul_f32 v[86:87], v[86:87], v[162:163] op_sel_hi:[1,0]
	v_pk_mul_f32 v[88:89], v[88:89], v[162:163] op_sel_hi:[1,0]
	v_pk_mul_f32 v[82:83], v[82:83], v[162:163] op_sel_hi:[1,0]
	v_pk_mul_f32 v[84:85], v[84:85], v[162:163] op_sel_hi:[1,0]
	v_cvt_pk_bf16_f32 v86, v86, v87
	v_cvt_pk_bf16_f32 v87, v88, v89
	v_cvt_pk_bf16_f32 v88, v82, v83
	v_cvt_pk_bf16_f32 v89, v84, v85
	v_add_u32_e32 v138, 0x10100, v136
	global_store_dwordx4 v138, v[86:89], s[8:9]
	v_pk_mul_f32 v[70:71], v[70:71], v[164:165] op_sel_hi:[1,0]
	v_pk_mul_f32 v[72:73], v[72:73], v[164:165] op_sel_hi:[1,0]
	v_pk_mul_f32 v[66:67], v[66:67], v[164:165] op_sel_hi:[1,0]
	v_pk_mul_f32 v[68:69], v[68:69], v[164:165] op_sel_hi:[1,0]
	v_cvt_pk_bf16_f32 v70, v70, v71
	v_cvt_pk_bf16_f32 v71, v72, v73
	v_cvt_pk_bf16_f32 v72, v66, v67
	v_cvt_pk_bf16_f32 v73, v68, v69
	v_add_u32_e32 v137, 0x18000, v136
	global_store_dwordx4 v137, v[70:73], s[8:9]
	v_pk_mul_f32 v[54:55], v[54:55], v[164:165] op_sel_hi:[1,0]
	v_pk_mul_f32 v[56:57], v[56:57], v[164:165] op_sel_hi:[1,0]
	v_pk_mul_f32 v[50:51], v[50:51], v[164:165] op_sel_hi:[1,0]
	v_pk_mul_f32 v[52:53], v[52:53], v[164:165] op_sel_hi:[1,0]
	v_cvt_pk_bf16_f32 v54, v54, v55
	v_cvt_pk_bf16_f32 v55, v56, v57
	v_cvt_pk_bf16_f32 v56, v50, v51
	v_cvt_pk_bf16_f32 v57, v52, v53
	v_add_u32_e32 v138, 0x18100, v136
	global_store_dwordx4 v138, v[54:57], s[8:9]
	v_pk_mul_f32 v[78:79], v[78:79], v[166:167] op_sel_hi:[1,0]
	v_pk_mul_f32 v[80:81], v[80:81], v[166:167] op_sel_hi:[1,0]
	v_pk_mul_f32 v[74:75], v[74:75], v[166:167] op_sel_hi:[1,0]
	v_pk_mul_f32 v[76:77], v[76:77], v[166:167] op_sel_hi:[1,0]
	v_cvt_pk_bf16_f32 v78, v78, v79
	v_cvt_pk_bf16_f32 v79, v80, v81
	v_cvt_pk_bf16_f32 v80, v74, v75
	v_cvt_pk_bf16_f32 v81, v76, v77
	v_add_u32_e32 v137, 0x40000, v136
	global_store_dwordx4 v137, v[78:81], s[8:9]
	v_pk_mul_f32 v[62:63], v[62:63], v[166:167] op_sel_hi:[1,0]
	v_pk_mul_f32 v[64:65], v[64:65], v[166:167] op_sel_hi:[1,0]
	v_pk_mul_f32 v[58:59], v[58:59], v[166:167] op_sel_hi:[1,0]
	v_pk_mul_f32 v[60:61], v[60:61], v[166:167] op_sel_hi:[1,0]
	v_cvt_pk_bf16_f32 v62, v62, v63
	v_cvt_pk_bf16_f32 v63, v64, v65
	v_cvt_pk_bf16_f32 v64, v58, v59
	v_cvt_pk_bf16_f32 v65, v60, v61
	v_add_u32_e32 v138, 0x40100, v136
	global_store_dwordx4 v138, v[62:65], s[8:9]
	v_pk_mul_f32 v[46:47], v[46:47], v[168:169] op_sel_hi:[1,0]
	v_pk_mul_f32 v[48:49], v[48:49], v[168:169] op_sel_hi:[1,0]
	v_pk_mul_f32 v[42:43], v[42:43], v[168:169] op_sel_hi:[1,0]
	v_pk_mul_f32 v[44:45], v[44:45], v[168:169] op_sel_hi:[1,0]
	v_cvt_pk_bf16_f32 v46, v46, v47
	v_cvt_pk_bf16_f32 v47, v48, v49
	v_cvt_pk_bf16_f32 v48, v42, v43
	v_cvt_pk_bf16_f32 v49, v44, v45
	v_add_u32_e32 v137, 0x48000, v136
	global_store_dwordx4 v137, v[46:49], s[8:9]
	v_pk_mul_f32 v[38:39], v[38:39], v[168:169] op_sel_hi:[1,0]
	v_pk_mul_f32 v[40:41], v[40:41], v[168:169] op_sel_hi:[1,0]
	v_pk_mul_f32 v[34:35], v[34:35], v[168:169] op_sel_hi:[1,0]
	v_pk_mul_f32 v[36:37], v[36:37], v[168:169] op_sel_hi:[1,0]
	v_cvt_pk_bf16_f32 v38, v38, v39
	v_cvt_pk_bf16_f32 v39, v40, v41
	v_cvt_pk_bf16_f32 v40, v34, v35
	v_cvt_pk_bf16_f32 v41, v36, v37
	v_add_u32_e32 v138, 0x48100, v136
	global_store_dwordx4 v138, v[38:41], s[8:9]
; __device__ __forceinline__ u32x4 pack8(const f32x4 a, const f32x4 b) { u32x4 w; w.x = cvt_pk_bf16(a[0], a[1]); w.y = cvt_pk_bf16(a[2], a[3]); w.z = cvt_pk_bf16(b[0], b[1]); w.w = cvt_pk_bf16(b[2], b[3]); return w; }
;     __device__ __forceinline__ void operator()(const Acc& acc, const Unit& u, int wr, int wc, int fr, int fq) const {
;     ...
; #pragma unroll
;                 for (int bj = 0; bj < 2; ++bj) {
;                     const size_t o = (size_t)row * DH + col0 + bj * HALF;
;                     f32x4 v0 = acc[ai][bj][m][0] * r, v1 = acc[ai][bj][m][1] * r;
;                     if (seg == 0) { *(u32x4*)(U + o) = pack8(v0, v1); }
	v_pk_mul_f32 v[30:31], v[30:31], v[170:171] op_sel_hi:[1,0]
	v_pk_mul_f32 v[32:33], v[32:33], v[170:171] op_sel_hi:[1,0]
	v_pk_mul_f32 v[26:27], v[26:27], v[170:171] op_sel_hi:[1,0]
	v_pk_mul_f32 v[28:29], v[28:29], v[170:171] op_sel_hi:[1,0]
	v_cvt_pk_bf16_f32 v30, v30, v31
	v_cvt_pk_bf16_f32 v31, v32, v33
	v_cvt_pk_bf16_f32 v32, v26, v27
	v_cvt_pk_bf16_f32 v33, v28, v29
	v_add_u32_e32 v137, 0x50000, v136
	global_store_dwordx4 v137, v[30:33], s[8:9]
	v_pk_mul_f32 v[22:23], v[22:23], v[170:171] op_sel_hi:[1,0]
	v_pk_mul_f32 v[24:25], v[24:25], v[170:171] op_sel_hi:[1,0]
	v_pk_mul_f32 v[18:19], v[18:19], v[170:171] op_sel_hi:[1,0]
	v_pk_mul_f32 v[20:21], v[20:21], v[170:171] op_sel_hi:[1,0]
	v_cvt_pk_bf16_f32 v22, v22, v23
	v_cvt_pk_bf16_f32 v23, v24, v25
	v_cvt_pk_bf16_f32 v24, v18, v19
	v_cvt_pk_bf16_f32 v25, v20, v21
	v_add_u32_e32 v138, 0x50100, v136
	global_store_dwordx4 v138, v[22:25], s[8:9]
	v_pk_mul_f32 v[14:15], v[14:15], v[172:173] op_sel_hi:[1,0]
	v_pk_mul_f32 v[16:17], v[16:17], v[172:173] op_sel_hi:[1,0]
	v_pk_mul_f32 v[10:11], v[10:11], v[172:173] op_sel_hi:[1,0]
	v_pk_mul_f32 v[12:13], v[12:13], v[172:173] op_sel_hi:[1,0]
	v_cvt_pk_bf16_f32 v14, v14, v15
	v_cvt_pk_bf16_f32 v15, v16, v17
	v_cvt_pk_bf16_f32 v16, v10, v11
	v_cvt_pk_bf16_f32 v17, v12, v13
	v_add_u32_e32 v137, 0x58000, v136
	global_store_dwordx4 v137, v[14:17], s[8:9]
	v_pk_mul_f32 v[6:7], v[6:7], v[172:173] op_sel_hi:[1,0]
	v_pk_mul_f32 v[8:9], v[8:9], v[172:173] op_sel_hi:[1,0]
	v_pk_mul_f32 v[2:3], v[2:3], v[172:173] op_sel_hi:[1,0]
	v_pk_mul_f32 v[4:5], v[4:5], v[172:173] op_sel_hi:[1,0]
	v_cvt_pk_bf16_f32 v6, v6, v7
	v_cvt_pk_bf16_f32 v7, v8, v9
	v_cvt_pk_bf16_f32 v8, v2, v3
	v_cvt_pk_bf16_f32 v9, v4, v5
	v_add_u32_e32 v138, 0x58100, v136
	global_store_dwordx4 v138, v[6:9], s[8:9]
	s_branch .Lep3_done
; __device__ __forceinline__ u32x4 pack8(const f32x4 a, const f32x4 b) { u32x4 w; w.x = cvt_pk_bf16(a[0], a[1]); w.y = cvt_pk_bf16(a[2], a[3]); w.z = cvt_pk_bf16(b[0], b[1]); w.w = cvt_pk_bf16(b[2], b[3]); return w; }
; #define PG8_BAR __builtin_amdgcn_s_barrier()
; template <class Epi, class Sched>
; __device__ __forceinline__ void gemm_phase(LAS unsigned char* lds, const Gemm g, const Sched& S, const Epi& E) {
;     ...
;         if (wr == 0) PG8_BAR;
;         E(acc, cur, wr, wc, fr, fq);
;         if (!has_next) break;
; #pragma unroll
;         for (int a = 0; a < 2; ++a)
; #pragma unroll
;             for (int b = 0; b < 2; ++b)
; #pragma unroll
;                 for (int m = 0; m < 4; ++m)
; #pragma unroll
;                     for (int n = 0; n < 2; ++n) acc[a][b][m][n] = (f32x4){0.f, 0.f, 0.f, 0.f};
;         cur = nxt; cA = nA; cB = nB; ++ui;
;         if (wr == 1) PG8_BAR;
;     __device__ __forceinline__ void operator()(const Acc& acc, const Unit& u, int wr, int wc, int fr, int fq) const {
;     ...
; #pragma unroll
;                 for (int bj = 0; bj < 2; ++bj) {
;                     const size_t o = (size_t)row * DH + col0 + bj * HALF;
;                     f32x4 v0 = acc[ai][bj][m][0] * r, v1 = acc[ai][bj][m][1] * r;
;                     if (seg == 0) { *(u32x4*)(U + o) = pack8(v0, v1); }
;                     else if (seg == 1) { *(f32x4*)(XL + o) = v0; *(f32x4*)(XL + o + 4) = v1; }
.Lep3_xl:
	v_lshlrev_b32_e32 v136, 2, v135
	v_pk_mul_f32 v[126:127], v[126:127], v[158:159] op_sel_hi:[1,0]
	v_pk_mul_f32 v[128:129], v[128:129], v[158:159] op_sel_hi:[1,0]
	v_pk_mul_f32 v[122:123], v[122:123], v[158:159] op_sel_hi:[1,0]
	v_pk_mul_f32 v[124:125], v[124:125], v[158:159] op_sel_hi:[1,0]
	global_store_dwordx4 v136, v[126:129], s[10:11]
	global_store_dwordx4 v136, v[122:125], s[10:11] offset:16
	v_pk_mul_f32 v[118:119], v[118:119], v[158:159] op_sel_hi:[1,0]
	v_pk_mul_f32 v[120:121], v[120:121], v[158:159] op_sel_hi:[1,0]
	v_pk_mul_f32 v[114:115], v[114:115], v[158:159] op_sel_hi:[1,0]
	v_pk_mul_f32 v[116:117], v[116:117], v[158:159] op_sel_hi:[1,0]
	global_store_dwordx4 v136, v[118:121], s[10:11] offset:512
	global_store_dwordx4 v136, v[114:117], s[10:11] offset:528
	v_add_u32_e32 v138, 0x10000, v136
	v_pk_mul_f32 v[110:111], v[110:111], v[160:161] op_sel_hi:[1,0]
	v_pk_mul_f32 v[112:113], v[112:113], v[160:161] op_sel_hi:[1,0]
	v_pk_mul_f32 v[106:107], v[106:107], v[160:161] op_sel_hi:[1,0]
	v_pk_mul_f32 v[108:109], v[108:109], v[160:161] op_sel_hi:[1,0]
	global_store_dwordx4 v138, v[110:113], s[10:11]
	global_store_dwordx4 v138, v[106:109], s[10:11] offset:16
	v_pk_mul_f32 v[102:103], v[102:103], v[160:161] op_sel_hi:[1,0]
	v_pk_mul_f32 v[104:105], v[104:105], v[160:161] op_sel_hi:[1,0]
	v_pk_mul_f32 v[98:99], v[98:99], v[160:161] op_sel_hi:[1,0]
	v_pk_mul_f32 v[100:101], v[100:101], v[160:161] op_sel_hi:[1,0]
	global_store_dwordx4 v138, v[102:105], s[10:11] offset:512
	global_store_dwordx4 v138, v[98:101], s[10:11] offset:528
	v_add_u32_e32 v137, 0x20000, v136
	v_pk_mul_f32 v[94:95], v[94:95], v[162:163] op_sel_hi:[1,0]
	v_pk_mul_f32 v[96:97], v[96:97], v[162:163] op_sel_hi:[1,0]
	v_pk_mul_f32 v[90:91], v[90:91], v[162:163] op_sel_hi:[1,0]
	v_pk_mul_f32 v[92:93], v[92:93], v[162:163] op_sel_hi:[1,0]
	global_store_dwordx4 v137, v[94:97], s[10:11]
	global_store_dwordx4 v137, v[90:93], s[10:11] offset:16
	v_pk_mul_f32 v[86:87], v[86:87], v[162:163] op_sel_hi:[1,0]
	v_pk_mul_f32 v[88:89], v[88:89], v[162:163] op_sel_hi:[1,0]
	v_pk_mul_f32 v[82:83], v[82:83], v[162:163] op_sel_hi:[1,0]
	v_pk_mul_f32 v[84:85], v[84:85], v[162:163] op_sel_hi:[1,0]
	global_store_dwordx4 v137, v[86:89], s[10:11] offset:512
	global_store_dwordx4 v137, v[82:85], s[10:11] offset:528
	v_add_u32_e32 v138, 0x30000, v136
	v_pk_mul_f32 v[70:71], v[70:71], v[164:165] op_sel_hi:[1,0]
	v_pk_mul_f32 v[72:73], v[72:73], v[164:165] op_sel_hi:[1,0]
	v_pk_mul_f32 v[66:67], v[66:67], v[164:165] op_sel_hi:[1,0]
	v_pk_mul_f32 v[68:69], v[68:69], v[164:165] op_sel_hi:[1,0]
	global_store_dwordx4 v138, v[70:73], s[10:11]
	global_store_dwordx4 v138, v[66:69], s[10:11] offset:16
	v_pk_mul_f32 v[54:55], v[54:55], v[164:165] op_sel_hi:[1,0]
	v_pk_mul_f32 v[56:57], v[56:57], v[164:165] op_sel_hi:[1,0]
	v_pk_mul_f32 v[50:51], v[50:51], v[164:165] op_sel_hi:[1,0]
	v_pk_mul_f32 v[52:53], v[52:53], v[164:165] op_sel_hi:[1,0]
	global_store_dwordx4 v138, v[54:57], s[10:11] offset:512
	global_store_dwordx4 v138, v[50:53], s[10:11] offset:528
	v_add_u32_e32 v137, 0x80000, v136
	v_pk_mul_f32 v[78:79], v[78:79], v[166:167] op_sel_hi:[1,0]
	v_pk_mul_f32 v[80:81], v[80:81], v[166:167] op_sel_hi:[1,0]
	v_pk_mul_f32 v[74:75], v[74:75], v[166:167] op_sel_hi:[1,0]
	v_pk_mul_f32 v[76:77], v[76:77], v[166:167] op_sel_hi:[1,0]
	global_store_dwordx4 v137, v[78:81], s[10:11]
	global_store_dwordx4 v137, v[74:77], s[10:11] offset:16
	v_pk_mul_f32 v[62:63], v[62:63], v[166:167] op_sel_hi:[1,0]
	v_pk_mul_f32 v[64:65], v[64:65], v[166:167] op_sel_hi:[1,0]
	v_pk_mul_f32 v[58:59], v[58:59], v[166:167] op_sel_hi:[1,0]
	v_pk_mul_f32 v[60:61], v[60:61], v[166:167] op_sel_hi:[1,0]
	global_store_dwordx4 v137, v[62:65], s[10:11] offset:512
	global_store_dwordx4 v137, v[58:61], s[10:11] offset:528
	v_add_u32_e32 v138, 0x90000, v136
	v_pk_mul_f32 v[46:47], v[46:47], v[168:169] op_sel_hi:[1,0]
	v_pk_mul_f32 v[48:49], v[48:49], v[168:169] op_sel_hi:[1,0]
	v_pk_mul_f32 v[42:43], v[42:43], v[168:169] op_sel_hi:[1,0]
	v_pk_mul_f32 v[44:45], v[44:45], v[168:169] op_sel_hi:[1,0]
	global_store_dwordx4 v138, v[46:49], s[10:11]
	global_store_dwordx4 v138, v[42:45], s[10:11] offset:16
	v_pk_mul_f32 v[38:39], v[38:39], v[168:169] op_sel_hi:[1,0]
	v_pk_mul_f32 v[40:41], v[40:41], v[168:169] op_sel_hi:[1,0]
	v_pk_mul_f32 v[34:35], v[34:35], v[168:169] op_sel_hi:[1,0]
	v_pk_mul_f32 v[36:37], v[36:37], v[168:169] op_sel_hi:[1,0]
	global_store_dwordx4 v138, v[38:41], s[10:11] offset:512
	global_store_dwordx4 v138, v[34:37], s[10:11] offset:528
	v_add_u32_e32 v137, 0xa0000, v136
	v_pk_mul_f32 v[30:31], v[30:31], v[170:171] op_sel_hi:[1,0]
	v_pk_mul_f32 v[32:33], v[32:33], v[170:171] op_sel_hi:[1,0]
	v_pk_mul_f32 v[26:27], v[26:27], v[170:171] op_sel_hi:[1,0]
	v_pk_mul_f32 v[28:29], v[28:29], v[170:171] op_sel_hi:[1,0]
	global_store_dwordx4 v137, v[30:33], s[10:11]
	global_store_dwordx4 v137, v[26:29], s[10:11] offset:16
	v_pk_mul_f32 v[22:23], v[22:23], v[170:171] op_sel_hi:[1,0]
	v_pk_mul_f32 v[24:25], v[24:25], v[170:171] op_sel_hi:[1,0]
	v_pk_mul_f32 v[18:19], v[18:19], v[170:171] op_sel_hi:[1,0]
	v_pk_mul_f32 v[20:21], v[20:21], v[170:171] op_sel_hi:[1,0]
	global_store_dwordx4 v137, v[22:25], s[10:11] offset:512
	global_store_dwordx4 v137, v[18:21], s[10:11] offset:528
	v_add_u32_e32 v138, 0xb0000, v136
	v_pk_mul_f32 v[14:15], v[14:15], v[172:173] op_sel_hi:[1,0]
	v_pk_mul_f32 v[16:17], v[16:17], v[172:173] op_sel_hi:[1,0]
	v_pk_mul_f32 v[10:11], v[10:11], v[172:173] op_sel_hi:[1,0]
	v_pk_mul_f32 v[12:13], v[12:13], v[172:173] op_sel_hi:[1,0]
	global_store_dwordx4 v138, v[14:17], s[10:11]
	global_store_dwordx4 v138, v[10:13], s[10:11] offset:16
	v_pk_mul_f32 v[6:7], v[6:7], v[172:173] op_sel_hi:[1,0]
	v_pk_mul_f32 v[8:9], v[8:9], v[172:173] op_sel_hi:[1,0]
	v_pk_mul_f32 v[2:3], v[2:3], v[172:173] op_sel_hi:[1,0]
	v_pk_mul_f32 v[4:5], v[4:5], v[172:173] op_sel_hi:[1,0]
	global_store_dwordx4 v138, v[6:9], s[10:11] offset:512
	global_store_dwordx4 v138, v[2:5], s[10:11] offset:528
.Lep3_done:
	s_andn2_b64 vcc, exec, s[92:93]
	s_mov_b64 s[4:5], -1
	s_cbranch_vccnz .LBB0_327
	s_branch .LBB0_496
.LBB0_496:
	s_andn2_b64 vcc, exec, s[54:55]
	s_cbranch_vccnz .LBB0_326
	s_barrier
	s_branch .LBB0_326
